# attention: rotated back edge with the next-tile prefetch issued behind the step's first K-fragment LDS reads (shorter pre-barrier path)
# baseline (speedup 1.0000x reference)
; __device__ __forceinline__ void attn_phase(LAS unsigned char* lds, const bf16_t* __restrict__ Q, const bf16_t* __restrict__ KN, const bf16_t* __restrict__ KR,
;                                            const bf16_t* __restrict__ VT, bf16_t* AO, int vcu, int G, int tid, int lane, int wave) {
;     ...
;                     attn_ldk(kf, kA);
.Lat_both_c:
	ds_read_b128 v[138:141], v1
	ds_read_b128 v[142:145], v1 offset:32
	ds_read_b128 v[146:149], v1 offset:64
	ds_read_b128 v[150:153], v1 offset:96
	ds_read_b128 v[154:157], v1 offset:128
	ds_read_b128 v[158:161], v1 offset:160
	ds_read_b128 v[162:165], v1 offset:6656
	ds_read_b128 v[166:169], v1 offset:6688
	s_cmp_lt_u32 s39, s36
	s_cbranch_scc0 .Lat_nopf_2
	s_mov_b32 s40, s39
	s_mov_b32 s41, 0
	s_lshl_b64 s[14:15], s[40:41], 17
	s_add_u32 s14, s10, s14
	s_addc_u32 s15, s11, s15
	global_load_dwordx4 v[228:231], v198, s[14:15]
	s_add_u32 s14, s14, 0x10000
	s_addc_u32 s15, s15, 0
	global_load_dwordx4 v[232:235], v198, s[14:15]
	s_lshl_b64 s[14:15], s[40:41], 13
	v_lshl_add_u64 v[250:251], v[208:209], 0, s[14:15]
	s_lshl_b64 s[14:15], s[40:41], 8
	v_lshl_add_u64 v[252:253], v[210:211], 0, s[14:15]
	global_load_dwordx4 v[236:239], v[250:251], off
	global_load_dwordx4 v[240:243], v[252:253], off
	global_load_dwordx4 v[244:247], v[252:253], off offset:128

; __device__ __forceinline__ void attn_phase(LAS unsigned char* lds, const bf16_t* __restrict__ Q, const bf16_t* __restrict__ KN, const bf16_t* __restrict__ KR,
;                                            const bf16_t* __restrict__ VT, bf16_t* AO, int vcu, int G, int tid, int lane, int wave) {
;     ...
;                     bf16x8 kf[12], vf[8], pa[4]; f32x16 a0, a1;
;                     PREFETCH_NEXT();
;                     attn_ldk(kf, kA);
.Lat_single_c:
	ds_read_b128 v[138:141], v1
	ds_read_b128 v[142:145], v1 offset:6656
	ds_read_b128 v[146:149], v1 offset:32
	ds_read_b128 v[150:153], v1 offset:6688
	ds_read_b128 v[154:157], v1 offset:64
	ds_read_b128 v[158:161], v1 offset:6720
	ds_read_b128 v[162:165], v1 offset:96
	ds_read_b128 v[166:169], v1 offset:6752
	s_cmp_lt_u32 s39, s36
	s_cbranch_scc0 .Lat_nopf_1
	s_mov_b32 s40, s39
	s_mov_b32 s41, 0
	s_lshl_b64 s[14:15], s[40:41], 17
	s_add_u32 s14, s10, s14
	s_addc_u32 s15, s11, s15
	global_load_dwordx4 v[228:231], v198, s[14:15]
	s_add_u32 s14, s14, 0x10000
	s_addc_u32 s15, s15, 0
	global_load_dwordx4 v[232:235], v198, s[14:15]
	s_lshl_b64 s[14:15], s[40:41], 13
	v_lshl_add_u64 v[250:251], v[208:209], 0, s[14:15]
	s_lshl_b64 s[14:15], s[40:41], 8
	v_lshl_add_u64 v[252:253], v[210:211], 0, s[14:15]
	global_load_dwordx4 v[236:239], v[250:251], off
	global_load_dwordx4 v[240:243], v[252:253], off
	global_load_dwordx4 v[244:247], v[252:253], off offset:128

; #define LAS __attribute__((address_space(3)))
; __device__ __forceinline__ void attn_phase(LAS unsigned char* lds, const bf16_t* __restrict__ Q, const bf16_t* __restrict__ KN, const bf16_t* __restrict__ KR,
;                                            const bf16_t* __restrict__ VT, bf16_t* AO, int vcu, int G, int tid, int lane, int wave) {
;     ...
;                 if (more) { LAS unsigned char* nb = lds + ((t + 1) & 1) * BUF;
;                     *(LAS u32x4*)(nb + kdst) = gk0; *(LAS u32x4*)(nb + kdst + 64 * KP * 2) = gk1; *(LAS u32x4*)(nb + rdst) = gr; *(LAS u32x4*)(nb + vdst) = gv0; *(LAS u32x4*)(nb + vdst + 128) = gv1; }
;                 __syncthreads();
;             }
.Lat_nostage:
	s_mov_b32 s8, s39
	s_cmp_lt_u32 s8, s36
	s_cbranch_scc0 .Lat_exit
	s_add_i32 s39, s8, 1
	s_bitcmp1_b32 s8, 0
	s_cselect_b32 s37, 0xac00, 0
	s_cselect_b32 s38, 0, 0xac00
	s_waitcnt lgkmcnt(0)
	v_add_u32_e32 v1, s37, v222
	v_add_u32_e32 v225, s37, v223
	s_lshl_b32 s40, s8, 1
	s_cmp_lt_u32 s40, s33
	s_cbranch_scc1 .Lat_both_b
	s_cmp_eq_u32 s40, s33
	s_cbranch_scc1 .Lat_single_b
	s_barrier
	s_branch .Lat_tail
